# attention: waves 4-7 raise priority from end of their PV(HF=1)+DMA run through top-of-tile and QK(HF=0) (one added s_setprio 1)
# baseline (speedup 1.0000x reference)
.LBB0_597:
	s_setprio 0
	s_waitcnt lgkmcnt(0)
	s_and_b64 vcc, exec, s[98:99]
	v_cvt_pk_bf16_f32 v96, v112, v113
	v_cvt_pk_bf16_f32 v97, v116, v115
	v_cvt_pk_bf16_f32 v98, v118, v119
	v_cvt_pk_bf16_f32 v99, v120, v117
	v_cvt_pk_bf16_f32 v100, v114, v121
	v_cvt_pk_bf16_f32 v101, v122, v123
	v_cvt_pk_bf16_f32 v102, v124, v125
	v_cvt_pk_bf16_f32 v103, v126, v127
	ds_read_b64_tr_b16 v[104:105], v244 offset:61440
	ds_read_b64_tr_b16 v[106:107], v244 offset:63488
	ds_read_b64_tr_b16 v[108:109], v245 offset:61440
	ds_read_b64_tr_b16 v[110:111], v245 offset:63488
	ds_read_b64_tr_b16 v[112:113], v246 offset:61440
	ds_read_b64_tr_b16 v[114:115], v246 offset:63488
	ds_read_b64_tr_b16 v[116:117], v247 offset:61440
	ds_read_b64_tr_b16 v[118:119], v247 offset:63488
	s_add_i32 s65, s65, 1
	s_add_u32 s36, s36, 0x10000
	s_addc_u32 s37, s37, 0
	s_addk_i32 s69, 0x4000
	s_add_i32 s70, s70, 64
	s_add_u32 s38, s38, 0x10000
	s_addc_u32 s39, s39, 0
	s_add_i32 s71, s71, 1
	s_add_i32 s46, s46, 1
	v_add_f32_e32 v162, v163, v162
	s_cbranch_vccz .Lat_lower
	s_mul_i32 s0, s65, 0xab
	s_bfe_u32 s0, s0, 0x70009
	s_mul_i32 s0, s0, 3
	s_sub_i32 s0, s65, s0
	s_and_b32 s0, s0, 0xff
	s_lshl_b32 s0, s0, 14
	s_add_i32 s0, s82, s0
	s_sub_u32 s100, s36, 0x4000
	s_subb_u32 s101, s37, 0
	s_waitcnt vmcnt(0) lgkmcnt(0)
	s_barrier
	v_mfma_f32_32x32x16_bf16 v[48:63], v[228:231], v[96:99], v[48:63]
	s_mov_b32 m0, s0
	s_add_i32 s1, s0, 0x2000
	global_load_lds_dwordx4 v174, s[36:37]
	v_mfma_f32_32x32x16_bf16 v[32:47], v[232:235], v[96:99], v[32:47]
	s_mov_b32 m0, s1
	s_add_i32 s1, s0, 0xfffff000
	global_load_lds_dwordx4 v180, s[36:37]
	v_mfma_f32_32x32x16_bf16 v[16:31], v[236:239], v[96:99], v[16:31]
	s_mov_b32 m0, s1
	s_add_i32 s1, s1, 0x2000
	global_load_lds_dwordx4 v174, s[100:101]
	v_mfma_f32_32x32x16_bf16 v[0:15], v[240:243], v[96:99], v[0:15]
	s_mov_b32 m0, s1
	s_and_b32 s0, s69, 0x4000
	s_add_i32 s0, s83, s0
	global_load_lds_dwordx4 v180, s[100:101]
	v_mfma_f32_32x32x16_bf16 v[48:63], v[104:107], v[100:103], v[48:63]
	s_mov_b32 m0, s0
	s_sub_u32 s100, s38, 0x4000
	s_subb_u32 s101, s39, 0
	s_add_i32 s1, s0, 0x2000
	global_load_lds_dwordx4 v175, s[38:39]
	v_mfma_f32_32x32x16_bf16 v[32:47], v[108:111], v[100:103], v[32:47]
	s_mov_b32 m0, s1
	s_add_i32 s1, s0, 0xfffff000
	global_load_lds_dwordx4 v181, s[38:39]
	v_mfma_f32_32x32x16_bf16 v[16:31], v[112:115], v[100:103], v[16:31]
	s_mov_b32 m0, s1
	s_add_i32 s1, s1, 0x2000
	global_load_lds_dwordx4 v175, s[100:101]
	v_mfma_f32_32x32x16_bf16 v[0:15], v[116:119], v[100:103], v[0:15]
	s_mov_b32 m0, s1
	s_nop 0
	global_load_lds_dwordx4 v181, s[100:101]
	s_setprio 1
	s_branch .Lat_join
